# P3 GDN prep: static s_setprio 1 for team 0 (waves 0-3) during the item loop, reset after
# speedup vs baseline: 1.0066x; 1.0066x over previous
.LBB0_447:
	v_mov_b32_e32 v102, v162
	s_load_dwordx2 s[6:7], s[0:1], 0xd8
	v_readfirstlane_b32 s54, v102
	s_nop 3
	s_cmpk_lt_u32 s54, 0x100
	s_cbranch_scc0 .Lp3_prio_done
	s_setprio 1
.Lp3_prio_done:
	s_waitcnt lgkmcnt(0)
	s_and_saveexec_b64 s[8:9], s[4:5]
	ds_add_u32 v169, v170 offset:36352
	s_or_b64 exec, exec, s[8:9]
	ds_read_b32 v2, v169 offset:36352
	s_add_i32 s55, s3, 4
	s_waitcnt lgkmcnt(0)
	v_cmp_gt_u32_e32 vcc, s55, v2
	s_and_saveexec_b64 s[8:9], vcc
	s_cbranch_execz .LBB0_452
	s_mov_b64 s[52:53], 0

.LBB0_524:
	s_setprio 0
	s_or_b64 exec, exec, s[10:11]
	s_cmpk_eq_i32 s33, 0x100
	s_cselect_b64 s[84:85], -1, 0
	s_cmpk_lg_i32 s33, 0x100
	v_lshlrev_b32_e32 v2, 4, v137
	s_cselect_b64 s[4:5], -1, 0
	v_and_b32_e32 v104, 15, v137
	v_and_b32_e32 v93, 0x70, v2
	v_lshrrev_b32_e32 v2, 4, v119
	v_writelane_b32 v255, s4, 7
	v_lshrrev_b32_e32 v105, 6, v137
	v_lshlrev_b32_e32 v99, 3, v2
	v_lshlrev_b32_e32 v106, 2, v2
	v_mul_u32_u24_e32 v2, 0x110, v104
	v_and_b32_e32 v3, 48, v119
	v_writelane_b32 v255, s5, 8
	s_movk_i32 s3, 0x200
	v_lshrrev_b32_e32 v94, 3, v137
	v_lshlrev_b32_e32 v71, 4, v105
	s_movk_i32 s4, 0x1ff
	v_add3_u32 v100, 0, v2, v3
	s_cmpk_lt_i32 s2, 0x200
	v_mov_b32_e32 v65, 0
	s_mov_b32 s89, 0
	v_lshl_add_u32 v91, v93, 1, 0
	v_mul_u32_u24_e32 v92, 0x110, v94
	v_add_u32_e32 v95, 64, v94
	v_cmp_lt_u32_e64 s[4:5], s4, v137
	v_cmp_gt_u32_e64 s[6:7], s3, v137
	v_or_b32_e32 v96, 0x80, v94
	v_lshl_add_u32 v90, v119, 1, 0
	v_or_b32_e32 v97, 64, v119
	v_or_b32_e32 v98, 0x80, v119
	v_lshrrev_b32_e32 v110, 7, v137
	v_or_b32_e32 v108, 32, v104
	v_add_u32_e32 v101, 0x2200, v100
	v_or_b32_e32 v109, 64, v104
	v_add_u32_e32 v102, 0x4400, v100
	v_or_b32_e32 v107, 0x60, v104
	v_add_u32_e32 v103, 0x6600, v100
	v_lshlrev_b32_e32 v60, 1, v71
	v_lshlrev_b32_e32 v62, 1, v93
	s_barrier
	v_readlane_b32 s3, v255, 41
	s_cmp_lg_u32 s3, 0
	s_cbranch_scc1 .Lswa_run
	s_cmpk_eq_i32 s33, 0x100
	s_cbranch_scc1 .LBB0_552
